# P0: residual-stream row loop starts at (wave+1024)%2048 so the waves with a 5th row are not the ones with a 3rd transpose item (on v66)
# speedup vs baseline: 1.0079x; 1.0079x over previous
.LBB0_8:
	s_addk_i32 s12, 0x400
	s_and_b32 s12, s12, 0x7ff
	s_cmpk_gt_i32 s12, 0x20ff
	s_cbranch_scc1 .LBB0_36
	v_mbcnt_lo_u32_b32 v1, -1, 0
	v_mbcnt_hi_u32_b32 v2, -1, v1
	v_and_b32_e32 v1, 64, v2
	v_add_u32_e32 v3, 64, v1
	v_xor_b32_e32 v1, 1, v2
	v_cmp_lt_i32_e32 vcc, v1, v3
	v_xor_b32_e32 v4, 2, v2
	v_lshlrev_b32_e32 v34, 2, v202
	v_cndmask_b32_e32 v1, v2, v1, vcc
	v_cmp_lt_i32_e32 vcc, v4, v3
	v_readlane_b32 s4, v252, 18
	v_mov_b32_e32 v35, 0
	v_cndmask_b32_e32 v4, v2, v4, vcc
	v_lshlrev_b32_e32 v39, 2, v4
	v_xor_b32_e32 v4, 4, v2
	v_cmp_lt_i32_e32 vcc, v4, v3
	v_readlane_b32 s5, v252, 19
	v_or_b32_e32 v6, 0x300, v34
	v_cndmask_b32_e32 v4, v2, v4, vcc
	v_lshlrev_b32_e32 v41, 2, v4
	v_xor_b32_e32 v4, 8, v2
	v_cmp_lt_i32_e32 vcc, v4, v3
	v_cmp_gt_u32_e64 s[8:9], 32, v202
	v_lshl_add_u64 v[36:37], s[4:5], 0, v[34:35]
	v_cndmask_b32_e32 v4, v2, v4, vcc
	v_lshlrev_b32_e32 v43, 2, v4
	v_xor_b32_e32 v4, 16, v2
	v_cmp_lt_i32_e32 vcc, v4, v3
	s_mov_b32 s15, 0
	v_cmp_eq_u32_e64 s[4:5], 0, v202
	v_cndmask_b32_e32 v4, v2, v4, vcc
	v_lshlrev_b32_e32 v45, 2, v4
	v_xor_b32_e32 v4, 32, v2
	v_cmp_lt_i32_e32 vcc, v4, v3
	v_lshlrev_b32_e32 v1, 2, v1
	v_or_b32_e32 v38, 0x400, v34
	v_cndmask_b32_e32 v2, v2, v4, vcc
	v_lshlrev_b32_e32 v46, 2, v2
	v_or_b32_e32 v2, 0x100, v34
	v_or_b32_e32 v4, 0x200, v34
	v_or_b32_e32 v40, 0x500, v34
	v_or_b32_e32 v42, 0x600, v34
	v_or_b32_e32 v44, 0x700, v34
	s_movk_i32 s26, 0x7fff
	s_mov_b32 s27, 0xffff0000
	v_lshlrev_b32_e32 v47, 1, v34
	v_lshlrev_b32_e32 v34, 2, v34
	v_lshlrev_b32_e32 v48, 1, v2
	v_lshlrev_b32_e32 v49, 1, v4
	v_lshlrev_b32_e32 v50, 1, v6
	s_branch .LBB0_11
